# P0: weight-conversion loop keeps the next item's 16 loads in flight while the current tile is processed (counted vmcnt ladders per path) + pipelined x row loop
# baseline (speedup 1.0000x reference)
; #define LAS __attribute__((address_space(3)))
; __device__ __forceinline__ unsigned pk2(float lo, float hi) { return f2bf(lo) | (f2bf(hi) << 16); }
; #define LDS_WAIT() asm volatile("s_waitcnt lgkmcnt(0)" ::: "memory")
; __device__ __forceinline__ void cv_process(const CvDesc& d, int lane, const f32x4 (&v)[16], const f32x4& g0, const f32x4& g1, LAS float* scr) {
;     const int nblk = d.N / 64, kb = d.r / nblk, nb = d.r % nblk, k0 = 64 * kb, n0 = 64 * nb;
;     const int lk = lane >> 4, n4 = (lane & 15) * 4, c = lane & 7;
; #pragma unroll
;     for (int j = 0; j < 16; ++j) { const int k = 4 * j + lk; *(LAS f32x4*)(scr + k * 64 + (n4 ^ (8 * ((k >> 3) & 7)))) = v[j]; }
;     LDS_WAIT(); asm volatile("" ::: "memory");
; #pragma unroll
;     for (int j = 0; j < 8; ++j) { const int n = (lane >> 3) + 8 * j; const LAS float* s = scr + (8 * c) * 64 + (n ^ (8 * c));
;         u32x4 o; o.x = pk2(s[0 * 64] * g0[0], s[1 * 64] * g0[1]); o.y = pk2(s[2 * 64] * g0[2], s[3 * 64] * g0[3]); o.z = pk2(s[4 * 64] * g1[0], s[5 * 64] * g1[1]); o.w = pk2(s[6 * 64] * g1[2], s[7 * 64] * g1[3]);
;         const int ng = n0 + n, drow = d.mode ? (((ng >> 7) << 8) + (ng & 127) + d.off) : (d.off + ng);
;         *(u32x4*)(d.dst + (size_t)drow * d.K + k0 + 8 * c) = o; }
.LBB0_141:
	s_or_b64 exec, exec, s[38:39]
	v_lshrrev_b32_e32 v4, 6, v201
	v_cvt_f32_u32_e32 v5, v4
	v_sub_u32_e32 v166, 0, v4
	v_sub_u32_e32 v165, 0, v205
	v_max_i32_e32 v165, v205, v165
	v_rcp_iflag_f32_e32 v5, v5
	s_cmp_eq_u32 s99, 1
	s_cbranch_scc1 .Lcv_ladB_next_inflight
	s_waitcnt vmcnt(23)
	ds_write_b128 v176, v[78:81]
	s_waitcnt vmcnt(22)
	ds_write_b128 v176, v[82:85] offset:1024
	s_waitcnt vmcnt(21)
	ds_write_b128 v177, v[86:89] offset:2048
	s_waitcnt vmcnt(20)
	ds_write_b128 v177, v[90:93] offset:3072
	s_waitcnt vmcnt(19)
	ds_write_b128 v178, v[94:97] offset:4096
	s_waitcnt vmcnt(18)
	ds_write_b128 v178, v[98:101] offset:5120
	s_waitcnt vmcnt(17)
	ds_write_b128 v179, v[106:109] offset:6144
	s_waitcnt vmcnt(16)
	ds_write_b128 v179, v[102:105] offset:7168
	s_waitcnt vmcnt(15)
	ds_write_b128 v180, v[110:113] offset:8192
	s_waitcnt vmcnt(14)
	ds_write_b128 v180, v[114:117] offset:9216
	s_waitcnt vmcnt(13)
	ds_write_b128 v181, v[118:121] offset:10240
	s_waitcnt vmcnt(12)
	ds_write_b128 v181, v[122:125] offset:11264
	s_waitcnt vmcnt(11)
	ds_write_b128 v182, v[126:129] offset:12288
	s_waitcnt vmcnt(10)
	ds_write_b128 v182, v[130:133] offset:13312
	s_waitcnt vmcnt(9)
	ds_write_b128 v183, v[134:137] offset:14336
	s_waitcnt vmcnt(8)
	ds_write_b128 v183, v[138:141] offset:15360
	s_branch .Lcv_ladB_done
.Lcv_ladB_next_inflight:
	s_waitcnt vmcnt(39)
	ds_write_b128 v176, v[78:81]
	s_waitcnt vmcnt(38)
	ds_write_b128 v176, v[82:85] offset:1024
	s_waitcnt vmcnt(37)
	ds_write_b128 v177, v[86:89] offset:2048
	s_waitcnt vmcnt(36)
	ds_write_b128 v177, v[90:93] offset:3072
	s_waitcnt vmcnt(35)
	ds_write_b128 v178, v[94:97] offset:4096
	s_waitcnt vmcnt(34)
	ds_write_b128 v178, v[98:101] offset:5120
	s_waitcnt vmcnt(33)
	ds_write_b128 v179, v[106:109] offset:6144
	s_waitcnt vmcnt(32)
	ds_write_b128 v179, v[102:105] offset:7168
	s_waitcnt vmcnt(31)
	ds_write_b128 v180, v[110:113] offset:8192
	s_waitcnt vmcnt(30)
	ds_write_b128 v180, v[114:117] offset:9216
	s_waitcnt vmcnt(29)
	ds_write_b128 v181, v[118:121] offset:10240
	s_waitcnt vmcnt(28)
	ds_write_b128 v181, v[122:125] offset:11264
	s_waitcnt vmcnt(27)
	ds_write_b128 v182, v[126:129] offset:12288
	s_waitcnt vmcnt(26)
	ds_write_b128 v182, v[130:133] offset:13312
	s_waitcnt vmcnt(25)
	ds_write_b128 v183, v[134:137] offset:14336
	s_waitcnt vmcnt(24)
	ds_write_b128 v183, v[138:141] offset:15360
.Lcv_ladB_done:
	v_ashrrev_i32_e32 v164, 31, v205
	s_waitcnt lgkmcnt(0)
	v_mul_f32_e32 v5, 0x4f7ffffe, v5
	v_cvt_u32_f32_e32 v5, v5
	v_mul_lo_u32 v166, v166, v5
	v_mul_hi_u32 v166, v5, v166
	v_add_u32_e32 v5, v5, v166
	v_mul_hi_u32 v5, v165, v5
	v_mul_lo_u32 v166, v5, v4
	v_sub_u32_e32 v165, v165, v166
	v_add_u32_e32 v167, 1, v5
	v_cmp_ge_u32_e64 s[4:5], v165, v4
	v_sub_u32_e32 v166, v165, v4
	s_nop 0
	v_cndmask_b32_e64 v5, v5, v167, s[4:5]
	v_cndmask_b32_e64 v165, v165, v166, s[4:5]
	v_add_u32_e32 v166, 1, v5
	v_cmp_ge_u32_e64 s[4:5], v165, v4
	s_nop 1
	v_cndmask_b32_e64 v5, v5, v166, s[4:5]
	v_xor_b32_e32 v5, v5, v164
	v_sub_u32_e32 v5, v5, v164
	ds_read2st64_b32 v[164:165], v185 offset1:1
	ds_read2st64_b32 v[168:169], v185 offset0:2 offset1:3
	v_mul_lo_u32 v4, v5, v4
	ds_read2st64_b32 v[208:209], v185 offset0:4 offset1:5
	ds_read2st64_b32 v[210:211], v185 offset0:6 offset1:7
	v_sub_u32_e32 v4, v205, v4
	v_lshlrev_b32_e32 v206, 6, v4
	v_lshlrev_b32_e32 v4, 7, v4
	v_lshlrev_b32_e32 v170, 6, v5
	v_and_b32_e32 v207, 0xffffff00, v4
	v_mov_b32_e32 v4, v142
	v_mov_b32_e32 v5, v144
	s_waitcnt lgkmcnt(3)
	v_mov_b32_e32 v166, v164
	s_waitcnt lgkmcnt(2)
	v_mov_b32_e32 v167, v168
	v_pk_mul_f32 v[212:213], v[4:5], v[166:167]
	v_mov_b32_e32 v166, v143
	v_mov_b32_e32 v167, v145
	v_mov_b32_e32 v168, v165
	v_pk_mul_f32 v[214:215], v[166:167], v[168:169]
	v_mov_b32_e32 v164, v146
	v_mov_b32_e32 v165, v148
	s_waitcnt lgkmcnt(1)
	v_mov_b32_e32 v168, v208
	s_waitcnt lgkmcnt(0)
	v_mov_b32_e32 v169, v210
	v_pk_mul_f32 v[216:217], v[164:165], v[168:169]
	v_mov_b32_e32 v168, v147
	v_mov_b32_e32 v169, v149
	v_mov_b32_e32 v210, v209
	v_pk_mul_f32 v[208:209], v[168:169], v[210:211]
	v_bfe_u32 v218, v215, 16, 1
	v_bfe_u32 v210, v209, 16, 1
	v_bfe_u32 v211, v208, 16, 1
	v_bfe_u32 v219, v214, 16, 1
	v_add3_u32 v215, v215, v218, s55
	v_add3_u32 v209, v209, v210, s55
	v_bfe_u32 v210, v212, 16, 1
	v_bfe_u32 v218, v216, 16, 1
	v_add3_u32 v214, v214, v219, s55
	v_add3_u32 v208, v208, v211, s55
	v_bfe_u32 v211, v213, 16, 1
	v_bfe_u32 v219, v217, 16, 1
	v_add3_u32 v216, v216, v218, s55
	v_add3_u32 v210, v212, v210, s55
	v_add3_u32 v217, v217, v219, s55
	v_add3_u32 v211, v213, v211, s55
	v_lshrrev_b32_e32 v212, 16, v210
	v_lshrrev_b32_e32 v210, 16, v216
	v_lshrrev_b32_e32 v213, 16, v211
	v_lshrrev_b32_e32 v211, 16, v217
	v_and_or_b32 v210, v208, s56, v210
	v_and_or_b32 v208, v214, s56, v212
	v_or_b32_e32 v212, v206, v184
	v_and_or_b32 v211, v209, s56, v211
	v_and_or_b32 v209, v215, s56, v213
	v_and_or_b32 v213, v212, s57, v207
	v_cmp_eq_u32_e64 s[4:5], 0, v203
	v_ashrrev_i32_e32 v171, 31, v170
	v_lshlrev_b64 v[170:171], 1, v[170:171]
	v_cndmask_b32_e64 v212, v213, v212, s[4:5]
	v_add_u32_e32 v212, v212, v204
	v_ashrrev_i32_e32 v215, 31, v212
	v_mad_u64_u32 v[212:213], s[0:1], v212, v202, 0
	v_mov_b32_e32 v214, v213
	v_mad_u64_u32 v[214:215], s[0:1], v215, v202, v[214:215]
	v_mov_b32_e32 v213, v214
	v_lshl_add_u64 v[212:213], v[212:213], 1, v[160:161]
	v_lshl_add_u64 v[212:213], v[212:213], 0, v[170:171]
	v_lshl_add_u64 v[212:213], v[212:213], 0, v[162:163]
	ds_read2st64_b32 v[214:215], v187 offset1:1
	ds_read2st64_b32 v[216:217], v187 offset0:2 offset1:3
	global_store_dwordx4 v[212:213], v[208:211], off
	ds_read2st64_b32 v[208:209], v187 offset0:4 offset1:5
	ds_read2st64_b32 v[210:211], v187 offset0:6 offset1:7
	s_waitcnt lgkmcnt(3)
; #define LAS __attribute__((address_space(3)))
; __device__ __forceinline__ unsigned pk2(float lo, float hi) { return f2bf(lo) | (f2bf(hi) << 16); }
; __device__ __forceinline__ void cv_process(const CvDesc& d, int lane, const f32x4 (&v)[16], const f32x4& g0, const f32x4& g1, LAS float* scr) {
;     ...
;     for (int j = 0; j < 8; ++j) { const int n = (lane >> 3) + 8 * j; const LAS float* s = scr + (8 * c) * 64 + (n ^ (8 * c));
;         u32x4 o; o.x = pk2(s[0 * 64] * g0[0], s[1 * 64] * g0[1]); o.y = pk2(s[2 * 64] * g0[2], s[3 * 64] * g0[3]); o.z = pk2(s[4 * 64] * g1[0], s[5 * 64] * g1[1]); o.w = pk2(s[6 * 64] * g1[2], s[7 * 64] * g1[3]);
;         const int ng = n0 + n, drow = d.mode ? (((ng >> 7) << 8) + (ng & 127) + d.off) : (d.off + ng);
;         *(u32x4*)(d.dst + (size_t)drow * d.K + k0 + 8 * c) = o; }
	v_mov_b32_e32 v212, v214
	s_waitcnt lgkmcnt(2)
	v_mov_b32_e32 v213, v216
	v_mov_b32_e32 v216, v215
	v_pk_mul_f32 v[214:215], v[166:167], v[216:217]
	s_waitcnt lgkmcnt(0)
	v_mov_b32_e32 v217, v210
	v_mov_b32_e32 v210, v209
	v_mov_b32_e32 v216, v208
	v_pk_mul_f32 v[208:209], v[168:169], v[210:211]
	v_pk_mul_f32 v[212:213], v[4:5], v[212:213]
	v_pk_mul_f32 v[216:217], v[164:165], v[216:217]
	v_bfe_u32 v210, v209, 16, 1
	v_bfe_u32 v218, v215, 16, 1
	v_bfe_u32 v211, v208, 16, 1
	v_bfe_u32 v219, v214, 16, 1
	v_add3_u32 v215, v215, v218, s55
	v_add3_u32 v209, v209, v210, s55
	v_bfe_u32 v210, v212, 16, 1
	v_bfe_u32 v218, v216, 16, 1
	v_add3_u32 v214, v214, v219, s55
	v_add3_u32 v208, v208, v211, s55
	v_bfe_u32 v211, v213, 16, 1
	v_bfe_u32 v219, v217, 16, 1
	v_add3_u32 v216, v216, v218, s55
	v_add3_u32 v210, v212, v210, s55
	v_add3_u32 v217, v217, v219, s55
	v_add3_u32 v211, v213, v211, s55
	v_lshrrev_b32_e32 v212, 16, v210
	v_lshrrev_b32_e32 v210, 16, v216
	v_lshrrev_b32_e32 v213, 16, v211
	v_lshrrev_b32_e32 v211, 16, v217
	v_and_or_b32 v210, v208, s56, v210
	v_and_or_b32 v208, v214, s56, v212
	v_or_b32_e32 v212, v206, v186
	v_and_or_b32 v211, v209, s56, v211
	v_and_or_b32 v209, v215, s56, v213
	v_and_or_b32 v213, v212, s62, v207
	v_cndmask_b32_e64 v212, v213, v212, s[4:5]
	v_add_u32_e32 v212, v212, v204
	v_ashrrev_i32_e32 v215, 31, v212
	v_mad_u64_u32 v[212:213], s[0:1], v212, v202, 0
	v_mov_b32_e32 v214, v213
	v_mad_u64_u32 v[214:215], s[0:1], v215, v202, v[214:215]
	v_mov_b32_e32 v213, v214
	v_lshl_add_u64 v[212:213], v[212:213], 1, v[160:161]
	v_lshl_add_u64 v[212:213], v[212:213], 0, v[170:171]
	v_lshl_add_u64 v[212:213], v[212:213], 0, v[162:163]
	ds_read2st64_b32 v[214:215], v189 offset1:1
	ds_read2st64_b32 v[216:217], v189 offset0:2 offset1:3
	global_store_dwordx4 v[212:213], v[208:211], off
	ds_read2st64_b32 v[208:209], v189 offset0:4 offset1:5
	ds_read2st64_b32 v[210:211], v189 offset0:6 offset1:7
	s_waitcnt lgkmcnt(3)
	v_mov_b32_e32 v212, v214
	s_waitcnt lgkmcnt(2)
	v_mov_b32_e32 v213, v216
	v_mov_b32_e32 v216, v215
	v_pk_mul_f32 v[214:215], v[166:167], v[216:217]
	s_waitcnt lgkmcnt(0)
	v_mov_b32_e32 v217, v210
	v_mov_b32_e32 v210, v209
	v_mov_b32_e32 v216, v208
	v_pk_mul_f32 v[208:209], v[168:169], v[210:211]
	v_pk_mul_f32 v[212:213], v[4:5], v[212:213]
	v_pk_mul_f32 v[216:217], v[164:165], v[216:217]
	v_bfe_u32 v210, v209, 16, 1
	v_bfe_u32 v218, v215, 16, 1
	v_bfe_u32 v211, v208, 16, 1
	v_bfe_u32 v219, v214, 16, 1
	v_add3_u32 v215, v215, v218, s55
	v_add3_u32 v209, v209, v210, s55
	v_bfe_u32 v210, v212, 16, 1
	v_bfe_u32 v218, v216, 16, 1
	v_add3_u32 v214, v214, v219, s55
	v_add3_u32 v208, v208, v211, s55
	v_bfe_u32 v211, v213, 16, 1
	v_bfe_u32 v219, v217, 16, 1
	v_add3_u32 v216, v216, v218, s55
	v_add3_u32 v210, v212, v210, s55
	v_add3_u32 v217, v217, v219, s55
	v_add3_u32 v211, v213, v211, s55
	v_lshrrev_b32_e32 v212, 16, v210
	v_lshrrev_b32_e32 v210, 16, v216
	v_lshrrev_b32_e32 v213, 16, v211
	v_lshrrev_b32_e32 v211, 16, v217
	v_and_or_b32 v210, v208, s56, v210
	v_and_or_b32 v208, v214, s56, v212
	v_or_b32_e32 v212, v206, v188
	v_and_or_b32 v211, v209, s56, v211
	v_and_or_b32 v209, v215, s56, v213
	v_and_or_b32 v213, v212, s63, v207
	v_cndmask_b32_e64 v212, v213, v212, s[4:5]
	v_add_u32_e32 v212, v212, v204
	v_ashrrev_i32_e32 v215, 31, v212
	v_mad_u64_u32 v[212:213], s[0:1], v212, v202, 0
	v_mov_b32_e32 v214, v213
	v_mad_u64_u32 v[214:215], s[0:1], v215, v202, v[214:215]
	v_mov_b32_e32 v213, v214
	v_lshl_add_u64 v[212:213], v[212:213], 1, v[160:161]
	v_lshl_add_u64 v[212:213], v[212:213], 0, v[170:171]
	v_lshl_add_u64 v[212:213], v[212:213], 0, v[162:163]
	ds_read2st64_b32 v[214:215], v191 offset1:1
	ds_read2st64_b32 v[216:217], v191 offset0:2 offset1:3
	global_store_dwordx4 v[212:213], v[208:211], off
	ds_read2st64_b32 v[208:209], v191 offset0:4 offset1:5
	ds_read2st64_b32 v[210:211], v191 offset0:6 offset1:7
	s_waitcnt lgkmcnt(3)
	v_mov_b32_e32 v212, v214
	s_waitcnt lgkmcnt(2)
	v_mov_b32_e32 v213, v216
	v_mov_b32_e32 v216, v215
	v_pk_mul_f32 v[214:215], v[166:167], v[216:217]
	s_waitcnt lgkmcnt(0)
	v_mov_b32_e32 v217, v210
	v_mov_b32_e32 v210, v209
	v_mov_b32_e32 v216, v208
	v_pk_mul_f32 v[208:209], v[168:169], v[210:211]
	v_pk_mul_f32 v[212:213], v[4:5], v[212:213]
	v_pk_mul_f32 v[216:217], v[164:165], v[216:217]
	v_bfe_u32 v210, v209, 16, 1
	v_bfe_u32 v218, v215, 16, 1
	v_bfe_u32 v211, v208, 16, 1
	v_bfe_u32 v219, v214, 16, 1
	v_add3_u32 v215, v215, v218, s55
	v_add3_u32 v209, v209, v210, s55
	v_bfe_u32 v210, v212, 16, 1
	v_bfe_u32 v218, v216, 16, 1
	v_add3_u32 v214, v214, v219, s55
	v_add3_u32 v208, v208, v211, s55
	v_bfe_u32 v211, v213, 16, 1
	v_bfe_u32 v219, v217, 16, 1
	v_add3_u32 v216, v216, v218, s55
	v_add3_u32 v210, v212, v210, s55
	v_add3_u32 v217, v217, v219, s55
	v_add3_u32 v211, v213, v211, s55
	v_lshrrev_b32_e32 v212, 16, v210
	v_lshrrev_b32_e32 v210, 16, v216
	v_lshrrev_b32_e32 v213, 16, v211
	v_lshrrev_b32_e32 v211, 16, v217
	v_and_or_b32 v210, v208, s56, v210
	v_and_or_b32 v208, v214, s56, v212
	v_or_b32_e32 v212, v206, v190
	v_and_or_b32 v211, v209, s56, v211
	v_and_or_b32 v209, v215, s56, v213
	v_and_or_b32 v213, v212, s64, v207
	v_cndmask_b32_e64 v212, v213, v212, s[4:5]
	v_add_u32_e32 v212, v212, v204
	v_ashrrev_i32_e32 v215, 31, v212
	v_mad_u64_u32 v[212:213], s[0:1], v212, v202, 0
	v_mov_b32_e32 v214, v213
	v_mad_u64_u32 v[214:215], s[0:1], v215, v202, v[214:215]
	v_mov_b32_e32 v213, v214
	v_lshl_add_u64 v[212:213], v[212:213], 1, v[160:161]
	v_lshl_add_u64 v[212:213], v[212:213], 0, v[170:171]
	v_lshl_add_u64 v[212:213], v[212:213], 0, v[162:163]
	ds_read2st64_b32 v[214:215], v193 offset1:1
	ds_read2st64_b32 v[216:217], v193 offset0:2 offset1:3
	global_store_dwordx4 v[212:213], v[208:211], off
	ds_read2st64_b32 v[208:209], v193 offset0:4 offset1:5
	ds_read2st64_b32 v[210:211], v193 offset0:6 offset1:7
	s_waitcnt lgkmcnt(3)
; #define LAS __attribute__((address_space(3)))
; __device__ __forceinline__ unsigned pk2(float lo, float hi) { return f2bf(lo) | (f2bf(hi) << 16); }
; __device__ __forceinline__ void cv_process(const CvDesc& d, int lane, const f32x4 (&v)[16], const f32x4& g0, const f32x4& g1, LAS float* scr) {
;     ...
;     for (int j = 0; j < 8; ++j) { const int n = (lane >> 3) + 8 * j; const LAS float* s = scr + (8 * c) * 64 + (n ^ (8 * c));
;         u32x4 o; o.x = pk2(s[0 * 64] * g0[0], s[1 * 64] * g0[1]); o.y = pk2(s[2 * 64] * g0[2], s[3 * 64] * g0[3]); o.z = pk2(s[4 * 64] * g1[0], s[5 * 64] * g1[1]); o.w = pk2(s[6 * 64] * g1[2], s[7 * 64] * g1[3]);
;         const int ng = n0 + n, drow = d.mode ? (((ng >> 7) << 8) + (ng & 127) + d.off) : (d.off + ng);
;         *(u32x4*)(d.dst + (size_t)drow * d.K + k0 + 8 * c) = o; }
	v_mov_b32_e32 v212, v214
	s_waitcnt lgkmcnt(2)
	v_mov_b32_e32 v213, v216
	v_mov_b32_e32 v216, v215
	v_pk_mul_f32 v[214:215], v[166:167], v[216:217]
	s_waitcnt lgkmcnt(0)
	v_mov_b32_e32 v217, v210
	v_mov_b32_e32 v210, v209
	v_mov_b32_e32 v216, v208
	v_pk_mul_f32 v[208:209], v[168:169], v[210:211]
	v_pk_mul_f32 v[212:213], v[4:5], v[212:213]
	v_pk_mul_f32 v[216:217], v[164:165], v[216:217]
	v_bfe_u32 v210, v209, 16, 1
	v_bfe_u32 v218, v215, 16, 1
	v_bfe_u32 v211, v208, 16, 1
	v_bfe_u32 v219, v214, 16, 1
	v_add3_u32 v215, v215, v218, s55
	v_add3_u32 v209, v209, v210, s55
	v_bfe_u32 v210, v212, 16, 1
	v_bfe_u32 v218, v216, 16, 1
	v_add3_u32 v214, v214, v219, s55
	v_add3_u32 v208, v208, v211, s55
	v_bfe_u32 v211, v213, 16, 1
	v_bfe_u32 v219, v217, 16, 1
	v_add3_u32 v216, v216, v218, s55
	v_add3_u32 v210, v212, v210, s55
	v_add3_u32 v217, v217, v219, s55
	v_add3_u32 v211, v213, v211, s55
	v_lshrrev_b32_e32 v212, 16, v210
	v_lshrrev_b32_e32 v210, 16, v216
	v_lshrrev_b32_e32 v213, 16, v211
	v_lshrrev_b32_e32 v211, 16, v217
	v_and_or_b32 v210, v208, s56, v210
	v_and_or_b32 v208, v214, s56, v212
	v_or_b32_e32 v212, v206, v192
	v_and_or_b32 v211, v209, s56, v211
	v_and_or_b32 v209, v215, s56, v213
	v_and_or_b32 v213, v212, s65, v207
	v_cndmask_b32_e64 v212, v213, v212, s[4:5]
	v_add_u32_e32 v212, v212, v204
	v_ashrrev_i32_e32 v215, 31, v212
	v_mad_u64_u32 v[212:213], s[0:1], v212, v202, 0
	v_mov_b32_e32 v214, v213
	v_mad_u64_u32 v[214:215], s[0:1], v215, v202, v[214:215]
	v_mov_b32_e32 v213, v214
	v_lshl_add_u64 v[212:213], v[212:213], 1, v[160:161]
	v_lshl_add_u64 v[212:213], v[212:213], 0, v[170:171]
	v_lshl_add_u64 v[212:213], v[212:213], 0, v[162:163]
	ds_read2st64_b32 v[214:215], v195 offset1:1
	ds_read2st64_b32 v[216:217], v195 offset0:2 offset1:3
	global_store_dwordx4 v[212:213], v[208:211], off
	ds_read2st64_b32 v[208:209], v195 offset0:4 offset1:5
	ds_read2st64_b32 v[210:211], v195 offset0:6 offset1:7
	s_waitcnt lgkmcnt(3)
	v_mov_b32_e32 v212, v214
	s_waitcnt lgkmcnt(2)
	v_mov_b32_e32 v213, v216
	v_mov_b32_e32 v216, v215
	v_pk_mul_f32 v[214:215], v[166:167], v[216:217]
	s_waitcnt lgkmcnt(0)
	v_mov_b32_e32 v217, v210
	v_mov_b32_e32 v210, v209
	v_mov_b32_e32 v216, v208
	v_pk_mul_f32 v[208:209], v[168:169], v[210:211]
	v_pk_mul_f32 v[212:213], v[4:5], v[212:213]
	v_pk_mul_f32 v[216:217], v[164:165], v[216:217]
	v_bfe_u32 v210, v209, 16, 1
	v_bfe_u32 v218, v215, 16, 1
	v_bfe_u32 v211, v208, 16, 1
	v_bfe_u32 v219, v214, 16, 1
	v_add3_u32 v215, v215, v218, s55
	v_add3_u32 v209, v209, v210, s55
	v_bfe_u32 v210, v212, 16, 1
	v_bfe_u32 v218, v216, 16, 1
	v_add3_u32 v214, v214, v219, s55
	v_add3_u32 v208, v208, v211, s55
	v_bfe_u32 v211, v213, 16, 1
	v_bfe_u32 v219, v217, 16, 1
	v_add3_u32 v216, v216, v218, s55
	v_add3_u32 v210, v212, v210, s55
	v_add3_u32 v217, v217, v219, s55
	v_add3_u32 v211, v213, v211, s55
	v_lshrrev_b32_e32 v212, 16, v210
	v_lshrrev_b32_e32 v210, 16, v216
	v_lshrrev_b32_e32 v213, 16, v211
	v_lshrrev_b32_e32 v211, 16, v217
	v_and_or_b32 v210, v208, s56, v210
	v_and_or_b32 v208, v214, s56, v212
	v_or_b32_e32 v212, v206, v194
	v_and_or_b32 v211, v209, s56, v211
	v_and_or_b32 v209, v215, s56, v213
	v_and_or_b32 v213, v212, s66, v207
	v_cndmask_b32_e64 v212, v213, v212, s[4:5]
	v_add_u32_e32 v212, v212, v204
	v_ashrrev_i32_e32 v215, 31, v212
	v_mad_u64_u32 v[212:213], s[0:1], v212, v202, 0
	v_mov_b32_e32 v214, v213
	v_mad_u64_u32 v[214:215], s[0:1], v215, v202, v[214:215]
	v_mov_b32_e32 v213, v214
	v_lshl_add_u64 v[212:213], v[212:213], 1, v[160:161]
	v_lshl_add_u64 v[212:213], v[212:213], 0, v[170:171]
	v_lshl_add_u64 v[212:213], v[212:213], 0, v[162:163]
	ds_read2st64_b32 v[214:215], v197 offset1:1
	ds_read2st64_b32 v[216:217], v197 offset0:2 offset1:3
	global_store_dwordx4 v[212:213], v[208:211], off
	ds_read2st64_b32 v[208:209], v197 offset0:4 offset1:5
	ds_read2st64_b32 v[210:211], v197 offset0:6 offset1:7
	s_waitcnt lgkmcnt(3)
; #define LAS __attribute__((address_space(3)))
; __device__ __forceinline__ unsigned pk2(float lo, float hi) { return f2bf(lo) | (f2bf(hi) << 16); }
; #define LDS_WAIT() asm volatile("s_waitcnt lgkmcnt(0)" ::: "memory")
; __device__ __forceinline__ void cv_process(const CvDesc& d, int lane, const f32x4 (&v)[16], const f32x4& g0, const f32x4& g1, LAS float* scr) {
;     ...
;     for (int j = 0; j < 8; ++j) { const int n = (lane >> 3) + 8 * j; const LAS float* s = scr + (8 * c) * 64 + (n ^ (8 * c));
;         u32x4 o; o.x = pk2(s[0 * 64] * g0[0], s[1 * 64] * g0[1]); o.y = pk2(s[2 * 64] * g0[2], s[3 * 64] * g0[3]); o.z = pk2(s[4 * 64] * g1[0], s[5 * 64] * g1[1]); o.w = pk2(s[6 * 64] * g1[2], s[7 * 64] * g1[3]);
;         const int ng = n0 + n, drow = d.mode ? (((ng >> 7) << 8) + (ng & 127) + d.off) : (d.off + ng);
;         *(u32x4*)(d.dst + (size_t)drow * d.K + k0 + 8 * c) = o; }
;     LDS_WAIT(); asm volatile("" ::: "memory");
	v_mov_b32_e32 v212, v214
	s_waitcnt lgkmcnt(2)
	v_mov_b32_e32 v213, v216
	v_mov_b32_e32 v216, v215
	v_pk_mul_f32 v[214:215], v[166:167], v[216:217]
	s_waitcnt lgkmcnt(0)
	v_mov_b32_e32 v217, v210
	v_mov_b32_e32 v210, v209
	v_mov_b32_e32 v216, v208
	v_pk_mul_f32 v[208:209], v[168:169], v[210:211]
	v_pk_mul_f32 v[212:213], v[4:5], v[212:213]
	v_pk_mul_f32 v[216:217], v[164:165], v[216:217]
	v_bfe_u32 v210, v209, 16, 1
	v_bfe_u32 v218, v215, 16, 1
	v_bfe_u32 v211, v208, 16, 1
	v_bfe_u32 v219, v214, 16, 1
	v_add3_u32 v215, v215, v218, s55
	v_add3_u32 v209, v209, v210, s55
	v_bfe_u32 v210, v212, 16, 1
	v_bfe_u32 v218, v216, 16, 1
	v_add3_u32 v214, v214, v219, s55
	v_add3_u32 v208, v208, v211, s55
	v_bfe_u32 v211, v213, 16, 1
	v_bfe_u32 v219, v217, 16, 1
	v_add3_u32 v216, v216, v218, s55
	v_add3_u32 v210, v212, v210, s55
	v_add3_u32 v217, v217, v219, s55
	v_add3_u32 v211, v213, v211, s55
	v_lshrrev_b32_e32 v212, 16, v210
	v_lshrrev_b32_e32 v210, 16, v216
	v_lshrrev_b32_e32 v213, 16, v211
	v_lshrrev_b32_e32 v211, 16, v217
	v_and_or_b32 v210, v208, s56, v210
	v_and_or_b32 v208, v214, s56, v212
	v_or_b32_e32 v212, v206, v196
	v_and_or_b32 v211, v209, s56, v211
	v_and_or_b32 v209, v215, s56, v213
	v_and_or_b32 v213, v212, s67, v207
	v_cndmask_b32_e64 v212, v213, v212, s[4:5]
	v_add_u32_e32 v212, v212, v204
	v_ashrrev_i32_e32 v215, 31, v212
	v_mad_u64_u32 v[212:213], s[0:1], v212, v202, 0
	v_mov_b32_e32 v214, v213
	v_mad_u64_u32 v[214:215], s[0:1], v215, v202, v[214:215]
	v_mov_b32_e32 v213, v214
	v_lshl_add_u64 v[212:213], v[212:213], 1, v[160:161]
	v_lshl_add_u64 v[212:213], v[212:213], 0, v[170:171]
	v_lshl_add_u64 v[212:213], v[212:213], 0, v[162:163]
	global_store_dwordx4 v[212:213], v[208:211], off
	ds_read2st64_b32 v[208:209], v199 offset1:1
	ds_read2st64_b32 v[210:211], v199 offset0:2 offset1:3
	ds_read2st64_b32 v[212:213], v199 offset0:4 offset1:5
	ds_read2st64_b32 v[214:215], v199 offset0:6 offset1:7
	v_or_b32_e32 v206, v206, v198
	v_and_or_b32 v207, v206, s54, v207
	v_cndmask_b32_e64 v206, v207, v206, s[4:5]
	v_add_u32_e32 v216, v206, v204
	s_waitcnt lgkmcnt(3)
	v_mov_b32_e32 v206, v209
	s_waitcnt lgkmcnt(2)
	v_mov_b32_e32 v207, v211
	v_pk_mul_f32 v[166:167], v[166:167], v[206:207]
	s_waitcnt lgkmcnt(1)
	v_mov_b32_e32 v206, v213
	s_waitcnt lgkmcnt(0)
	v_mov_b32_e32 v207, v215
	v_mov_b32_e32 v209, v210
	v_pk_mul_f32 v[168:169], v[168:169], v[206:207]
	v_mov_b32_e32 v213, v214
	v_pk_mul_f32 v[4:5], v[4:5], v[208:209]
	v_pk_mul_f32 v[164:165], v[164:165], v[212:213]
	v_bfe_u32 v206, v169, 16, 1
	v_bfe_u32 v207, v168, 16, 1
	v_bfe_u32 v208, v167, 16, 1
	v_bfe_u32 v209, v166, 16, 1
	v_add3_u32 v209, v166, v209, s55
	v_add3_u32 v208, v167, v208, s55
	v_add3_u32 v166, v168, v207, s55
	v_add3_u32 v167, v169, v206, s55
	v_bfe_u32 v168, v4, 16, 1
	v_bfe_u32 v169, v5, 16, 1
	v_bfe_u32 v206, v164, 16, 1
	v_bfe_u32 v207, v165, 16, 1
	v_add3_u32 v165, v165, v207, s55
	v_add3_u32 v164, v164, v206, s55
	v_add3_u32 v5, v5, v169, s55
	v_add3_u32 v4, v4, v168, s55
	v_lshrrev_b32_e32 v4, 16, v4
	v_lshrrev_b32_e32 v5, 16, v5
	v_lshrrev_b32_e32 v164, 16, v164
	v_lshrrev_b32_e32 v165, 16, v165
	v_and_or_b32 v167, v167, s56, v165
	v_and_or_b32 v166, v166, s56, v164
	v_and_or_b32 v165, v208, s56, v5
	v_and_or_b32 v164, v209, s56, v4
	v_mad_u64_u32 v[4:5], s[0:1], v216, v202, 0
	v_ashrrev_i32_e32 v169, 31, v216
	v_mov_b32_e32 v168, v5
	v_mad_u64_u32 v[168:169], s[0:1], v169, v202, v[168:169]
	v_mov_b32_e32 v5, v168
	v_lshl_add_u64 v[4:5], v[4:5], 1, v[160:161]
	v_lshl_add_u64 v[4:5], v[4:5], 0, v[170:171]
	v_lshl_add_u64 v[4:5], v[4:5], 0, v[162:163]
	global_store_dwordx4 v[4:5], v[164:167], off
	s_waitcnt lgkmcnt(0)
	s_and_b64 s[0:1], vcc, exec

; #define PLE_JOBS(L) \
;     JOB(CV_DD, a.in[12] + (size_t)(L) * D * D, D, D, ws + WS_WG + (size_t)(L) * SZ_WG, a.in[11] + (L) * D, 0, 0) \
;     JOB(CV_PJ, a.in[13] + (size_t)(L) * PLE * D, PLE, D, ws + WS_WP + (size_t)(L) * SZ_WP, nullptr, 0, 0)
; __device__ __forceinline__ CvDesc cv_decode(const Args& a, int it) {
;     ...
;     int r = it; CvDesc d; d.src = nullptr; d.dst = nullptr; d.gain = nullptr; d.K = 64; d.N = 64; d.mode = 0; d.off = 0; d.r = 0; bool hit = false;
;     ...
;     FFN_JOBS(0, 0, 3, 4, 5, 2) FFN_JOBS(1, 0, 8, 9, 10, 7) PLE_JOBS(0)
; __device__ __forceinline__ void convert_items(const Args& a, LAS unsigned char* lds, int first, int last, int worker, int nworkers) {
;     ...
;         const int it1 = it + nworkers; const bool h1 = it1 < last;
;         if (h1) { d1 = cv_decode(a, it1); cv_load(d1, lane, vb, gb0, gb1); }
.LBB0_143:
	s_mov_b32 s98, 0
	v_add_u32_e32 v206, s42, v3
	v_cmp_gt_i32_e32 vcc, s3, v206
	s_and_saveexec_b64 s[36:37], vcc
	s_cbranch_execz .LBB0_231
	s_mov_b32 s98, 1
	v_cmp_lt_i32_e64 s[4:5], s43, v206
	v_mov_b32_e32 v203, 1
	v_mov_b32_e32 v202, 0x800
	v_mov_b32_e32 v201, 0x1600
	v_mov_b64_e32 v[4:5], s[8:9]
	v_mov_b64_e32 v[160:161], s[44:45]
	v_mov_b64_e32 v[134:135], s[10:11]
	v_mov_b32_e32 v205, v206
	v_mov_b32_e32 v84, v206
	s_and_saveexec_b64 s[0:1], s[4:5]
	v_add_u32_e32 v84, 0xfffff500, v206
	v_mov_b32_e32 v203, 0
	v_mov_b64_e32 v[4:5], 0
	v_mov_b32_e32 v201, 64
	v_mov_b32_e32 v202, 64
	v_mov_b64_e32 v[160:161], 0
	v_mov_b64_e32 v[134:135], 0
	v_mov_b32_e32 v205, 0
	s_or_b64 exec, exec, s[0:1]
	s_mov_b64 s[38:39], -1
	v_mov_b32_e32 v204, 0
	s_mov_b64 s[46:47], -1
	s_and_saveexec_b64 s[0:1], s[4:5]
	s_cbranch_execz .LBB0_150
	v_cmp_lt_i32_e64 s[4:5], s43, v84
	v_mov_b32_e32 v88, 0x1600
	v_mov_b32_e32 v87, 0x800
	v_mov_b32_e32 v85, 1
	v_mov_b32_e32 v204, 0x80
	v_mov_b64_e32 v[78:79], s[12:13]
	v_mov_b64_e32 v[80:81], s[44:45]
	v_mov_b64_e32 v[82:83], s[8:9]
	v_mov_b32_e32 v86, v84
	s_and_saveexec_b64 s[50:51], s[4:5]
	s_cbranch_execz .LBB0_149
	v_add_u32_e32 v84, 0xfffff500, v84
	v_mov_b32_e32 v204, 0
	s_xor_b64 s[46:47], exec, -1
	v_mov_b32_e32 v86, v205
	v_mov_b32_e32 v85, v203
	v_mov_b64_e32 v[78:79], v[134:135]
	v_mov_b64_e32 v[80:81], v[160:161]
	v_mov_b64_e32 v[82:83], v[4:5]
	v_mov_b32_e32 v87, v202
	v_mov_b32_e32 v88, v201

; #define LAS __attribute__((address_space(3)))
; __device__ __forceinline__ unsigned pk2(float lo, float hi) { return f2bf(lo) | (f2bf(hi) << 16); }
; #define LDS_WAIT() asm volatile("s_waitcnt lgkmcnt(0)" ::: "memory")
; __device__ __forceinline__ void cv_process(const CvDesc& d, int lane, const f32x4 (&v)[16], const f32x4& g0, const f32x4& g1, LAS float* scr) {
;     const int nblk = d.N / 64, kb = d.r / nblk, nb = d.r % nblk, k0 = 64 * kb, n0 = 64 * nb;
;     const int lk = lane >> 4, n4 = (lane & 15) * 4, c = lane & 7;
; #pragma unroll
;     for (int j = 0; j < 16; ++j) { const int k = 4 * j + lk; *(LAS f32x4*)(scr + k * 64 + (n4 ^ (8 * ((k >> 3) & 7)))) = v[j]; }
;     LDS_WAIT(); asm volatile("" ::: "memory");
; #pragma unroll
;     for (int j = 0; j < 8; ++j) { const int n = (lane >> 3) + 8 * j; const LAS float* s = scr + (8 * c) * 64 + (n ^ (8 * c));
;         u32x4 o; o.x = pk2(s[0 * 64] * g0[0], s[1 * 64] * g0[1]); o.y = pk2(s[2 * 64] * g0[2], s[3 * 64] * g0[3]); o.z = pk2(s[4 * 64] * g1[0], s[5 * 64] * g1[1]); o.w = pk2(s[6 * 64] * g1[2], s[7 * 64] * g1[3]);
;         const int ng = n0 + n, drow = d.mode ? (((ng >> 7) << 8) + (ng & 127) + d.off) : (d.off + ng);
;         *(u32x4*)(d.dst + (size_t)drow * d.K + k0 + 8 * c) = o; }
.LBB0_231:
	s_or_b64 exec, exec, s[36:37]
	v_lshrrev_b32_e32 v4, 6, v151
	v_cvt_f32_u32_e32 v5, v4
	v_sub_u32_e32 v164, 0, v4
	v_sub_u32_e32 v163, 0, v174
	v_max_i32_e32 v163, v174, v163
	v_rcp_iflag_f32_e32 v5, v5
	s_cmp_eq_u32 s98, 1
	s_cbranch_scc1 .Lcv_ladA_next_inflight
	s_waitcnt vmcnt(15)
	ds_write_b128 v176, v[6:9]
	s_waitcnt vmcnt(14)
	ds_write_b128 v176, v[10:13] offset:1024
	s_waitcnt vmcnt(13)
	ds_write_b128 v177, v[14:17] offset:2048
	s_waitcnt vmcnt(12)
	ds_write_b128 v177, v[18:21] offset:3072
	s_waitcnt vmcnt(11)
	ds_write_b128 v178, v[22:25] offset:4096
	s_waitcnt vmcnt(10)
	ds_write_b128 v178, v[26:29] offset:5120
	s_waitcnt vmcnt(9)
	ds_write_b128 v179, v[30:33] offset:6144
	s_waitcnt vmcnt(8)
	ds_write_b128 v179, v[34:37] offset:7168
	s_waitcnt vmcnt(7)
	ds_write_b128 v180, v[38:41] offset:8192
	s_waitcnt vmcnt(6)
	ds_write_b128 v180, v[42:45] offset:9216
	s_waitcnt vmcnt(5)
	ds_write_b128 v181, v[46:49] offset:10240
	s_waitcnt vmcnt(4)
	ds_write_b128 v181, v[50:53] offset:11264
	s_waitcnt vmcnt(3)
	ds_write_b128 v182, v[54:57] offset:12288
	s_waitcnt vmcnt(2)
	ds_write_b128 v182, v[58:61] offset:13312
	s_waitcnt vmcnt(1)
	ds_write_b128 v183, v[62:65] offset:14336
	s_waitcnt vmcnt(0)
	ds_write_b128 v183, v[66:69] offset:15360
	s_branch .Lcv_ladA_done
.Lcv_ladA_next_inflight:
	s_waitcnt vmcnt(31)
	ds_write_b128 v176, v[6:9]
	s_waitcnt vmcnt(30)
	ds_write_b128 v176, v[10:13] offset:1024
	s_waitcnt vmcnt(29)
	ds_write_b128 v177, v[14:17] offset:2048
	s_waitcnt vmcnt(28)
	ds_write_b128 v177, v[18:21] offset:3072
	s_waitcnt vmcnt(27)
	ds_write_b128 v178, v[22:25] offset:4096
	s_waitcnt vmcnt(26)
	ds_write_b128 v178, v[26:29] offset:5120
	s_waitcnt vmcnt(25)
	ds_write_b128 v179, v[30:33] offset:6144
	s_waitcnt vmcnt(24)
	ds_write_b128 v179, v[34:37] offset:7168
	s_waitcnt vmcnt(23)
	ds_write_b128 v180, v[38:41] offset:8192
	s_waitcnt vmcnt(22)
	ds_write_b128 v180, v[42:45] offset:9216
	s_waitcnt vmcnt(21)
	ds_write_b128 v181, v[46:49] offset:10240
	s_waitcnt vmcnt(20)
	ds_write_b128 v181, v[50:53] offset:11264
	s_waitcnt vmcnt(19)
	ds_write_b128 v182, v[54:57] offset:12288
	s_waitcnt vmcnt(18)
	ds_write_b128 v182, v[58:61] offset:13312
	s_waitcnt vmcnt(17)
	ds_write_b128 v183, v[62:65] offset:14336
	s_waitcnt vmcnt(16)
	ds_write_b128 v183, v[66:69] offset:15360
.Lcv_ladA_done:
	s_waitcnt lgkmcnt(0)
	v_ashrrev_i32_e32 v162, 31, v174
	v_mul_f32_e32 v5, 0x4f7ffffe, v5
	v_cvt_u32_f32_e32 v5, v5
	v_mul_lo_u32 v164, v164, v5
	v_mul_hi_u32 v164, v5, v164
	v_add_u32_e32 v5, v5, v164
	v_mul_hi_u32 v5, v163, v5
	v_mul_lo_u32 v164, v5, v4
	v_sub_u32_e32 v163, v163, v164
	v_add_u32_e32 v165, 1, v5
	v_cmp_ge_u32_e64 s[4:5], v163, v4
	v_sub_u32_e32 v164, v163, v4
	s_nop 0
	v_cndmask_b32_e64 v5, v5, v165, s[4:5]
	v_cndmask_b32_e64 v163, v163, v164, s[4:5]
	v_add_u32_e32 v164, 1, v5
	v_cmp_ge_u32_e64 s[4:5], v163, v4
	s_nop 1
	v_cndmask_b32_e64 v5, v5, v164, s[4:5]
	v_xor_b32_e32 v5, v5, v162
	ds_read2st64_b32 v[164:165], v185 offset1:1
	ds_read2st64_b32 v[168:169], v185 offset0:2 offset1:3
	v_sub_u32_e32 v5, v5, v162
	v_mul_lo_u32 v4, v5, v4
	ds_read2st64_b32 v[170:171], v185 offset0:4 offset1:5
	ds_read2st64_b32 v[210:211], v185 offset0:6 offset1:7
	v_sub_u32_e32 v4, v174, v4
	v_lshlrev_b32_e32 v207, 6, v4
	v_lshlrev_b32_e32 v4, 7, v4
	v_lshlrev_b32_e32 v162, 6, v5
	v_and_b32_e32 v208, 0xffffff00, v4
	v_mov_b32_e32 v4, v70
	v_mov_b32_e32 v5, v72
	s_waitcnt lgkmcnt(3)
	v_mov_b32_e32 v166, v164
	s_waitcnt lgkmcnt(2)
	v_mov_b32_e32 v167, v168
	v_pk_mul_f32 v[212:213], v[4:5], v[166:167]
	v_mov_b32_e32 v166, v71
	v_mov_b32_e32 v167, v73
	v_mov_b32_e32 v168, v165
	v_pk_mul_f32 v[214:215], v[166:167], v[168:169]
	v_mov_b32_e32 v164, v74
	v_mov_b32_e32 v165, v76
	s_waitcnt lgkmcnt(1)
	v_mov_b32_e32 v168, v170
	s_waitcnt lgkmcnt(0)
	v_mov_b32_e32 v169, v210
	v_pk_mul_f32 v[216:217], v[164:165], v[168:169]
	v_mov_b32_e32 v168, v75
	v_mov_b32_e32 v169, v77
	v_mov_b32_e32 v210, v171
	v_pk_mul_f32 v[170:171], v[168:169], v[210:211]
	v_bfe_u32 v211, v215, 16, 1
	v_bfe_u32 v209, v171, 16, 1
	v_bfe_u32 v218, v214, 16, 1
	v_add3_u32 v211, v215, v211, s55
	v_bfe_u32 v215, v216, 16, 1
	v_bfe_u32 v210, v170, 16, 1
	v_add3_u32 v214, v214, v218, s55
	v_add3_u32 v171, v171, v209, s55
	v_bfe_u32 v209, v212, 16, 1
	v_bfe_u32 v218, v217, 16, 1
	v_add3_u32 v215, v216, v215, s55
	v_add3_u32 v170, v170, v210, s55
	v_bfe_u32 v210, v213, 16, 1
	v_add3_u32 v217, v217, v218, s55
	v_add3_u32 v209, v212, v209, s55
	v_lshrrev_b32_e32 v212, 16, v215
	v_add3_u32 v210, v213, v210, s55
	v_lshrrev_b32_e32 v213, 16, v217
	v_and_or_b32 v212, v170, s56, v212
	v_or_b32_e32 v170, v207, v184
	v_and_or_b32 v213, v171, s56, v213
	v_and_or_b32 v171, v170, s57, v208
	v_cmp_eq_u32_e64 s[4:5], 0, v172
	v_lshrrev_b32_e32 v209, 16, v209
	v_lshrrev_b32_e32 v210, 16, v210
	v_cndmask_b32_e64 v170, v171, v170, s[4:5]
	v_add_u32_e32 v170, v170, v173
	v_and_or_b32 v211, v211, s56, v210
	v_and_or_b32 v210, v214, s56, v209
	v_ashrrev_i32_e32 v209, 31, v170
	v_mad_u64_u32 v[170:171], s[0:1], v170, v153, 0
	v_mov_b32_e32 v214, v171
	v_mad_u64_u32 v[214:215], s[0:1], v209, v153, v[214:215]
	v_ashrrev_i32_e32 v163, 31, v162
	v_mov_b32_e32 v171, v214
	v_lshl_add_u64 v[214:215], v[170:171], 1, v[154:155]
	v_lshlrev_b64 v[170:171], 1, v[162:163]
	v_lshl_add_u64 v[214:215], v[214:215], 0, v[170:171]
	v_lshlrev_b64 v[162:163], 1, v[158:159]
	v_lshl_add_u64 v[214:215], v[214:215], 0, v[162:163]
	ds_read2st64_b32 v[216:217], v187 offset1:1
	ds_read2st64_b32 v[218:219], v187 offset0:2 offset1:3
	global_store_dwordx4 v[214:215], v[210:213], off
	ds_read2st64_b32 v[210:211], v187 offset0:4 offset1:5
	ds_read2st64_b32 v[212:213], v187 offset0:6 offset1:7
	s_waitcnt lgkmcnt(3)
; #define LAS __attribute__((address_space(3)))
; __device__ __forceinline__ unsigned pk2(float lo, float hi) { return f2bf(lo) | (f2bf(hi) << 16); }
; __device__ __forceinline__ void cv_process(const CvDesc& d, int lane, const f32x4 (&v)[16], const f32x4& g0, const f32x4& g1, LAS float* scr) {
;     ...
;     for (int j = 0; j < 8; ++j) { const int n = (lane >> 3) + 8 * j; const LAS float* s = scr + (8 * c) * 64 + (n ^ (8 * c));
;         u32x4 o; o.x = pk2(s[0 * 64] * g0[0], s[1 * 64] * g0[1]); o.y = pk2(s[2 * 64] * g0[2], s[3 * 64] * g0[3]); o.z = pk2(s[4 * 64] * g1[0], s[5 * 64] * g1[1]); o.w = pk2(s[6 * 64] * g1[2], s[7 * 64] * g1[3]);
;         const int ng = n0 + n, drow = d.mode ? (((ng >> 7) << 8) + (ng & 127) + d.off) : (d.off + ng);
;         *(u32x4*)(d.dst + (size_t)drow * d.K + k0 + 8 * c) = o; }
	v_mov_b32_e32 v214, v216
	s_waitcnt lgkmcnt(2)
	v_mov_b32_e32 v215, v218
	v_mov_b32_e32 v218, v217
	v_pk_mul_f32 v[216:217], v[166:167], v[218:219]
	s_waitcnt lgkmcnt(0)
	v_mov_b32_e32 v219, v212
	v_mov_b32_e32 v212, v211
	v_mov_b32_e32 v218, v210
	v_pk_mul_f32 v[210:211], v[168:169], v[212:213]
	v_pk_mul_f32 v[214:215], v[4:5], v[214:215]
	v_pk_mul_f32 v[218:219], v[164:165], v[218:219]
	v_bfe_u32 v209, v211, 16, 1
	v_bfe_u32 v212, v210, 16, 1
	v_bfe_u32 v213, v217, 16, 1
	v_bfe_u32 v220, v216, 16, 1
	v_add3_u32 v216, v216, v220, s55
	v_add3_u32 v217, v217, v213, s55
	v_add3_u32 v210, v210, v212, s55
	v_add3_u32 v209, v211, v209, s55
	v_bfe_u32 v211, v214, 16, 1
	v_bfe_u32 v212, v215, 16, 1
	v_bfe_u32 v213, v218, 16, 1
	v_bfe_u32 v220, v219, 16, 1
	v_add3_u32 v219, v219, v220, s55
	v_add3_u32 v213, v218, v213, s55
	v_add3_u32 v212, v215, v212, s55
	v_add3_u32 v211, v214, v211, s55
	v_lshrrev_b32_e32 v214, 16, v211
	v_lshrrev_b32_e32 v211, 16, v212
	v_lshrrev_b32_e32 v212, 16, v213
	v_lshrrev_b32_e32 v213, 16, v219
	v_and_or_b32 v213, v209, s56, v213
	v_or_b32_e32 v209, v207, v186
	v_and_or_b32 v212, v210, s56, v212
	v_and_or_b32 v210, v216, s56, v214
	v_and_or_b32 v214, v209, s62, v208
	v_cndmask_b32_e64 v209, v214, v209, s[4:5]
	v_add_u32_e32 v209, v209, v173
	v_mad_u64_u32 v[214:215], s[0:1], v209, v153, 0
	v_and_or_b32 v211, v217, s56, v211
	v_ashrrev_i32_e32 v217, 31, v209
	v_mov_b32_e32 v216, v215
	v_mad_u64_u32 v[216:217], s[0:1], v217, v153, v[216:217]
	v_mov_b32_e32 v215, v216
	v_lshl_add_u64 v[214:215], v[214:215], 1, v[154:155]
	v_lshl_add_u64 v[214:215], v[214:215], 0, v[170:171]
	v_lshl_add_u64 v[214:215], v[214:215], 0, v[162:163]
	ds_read2st64_b32 v[216:217], v189 offset1:1
	ds_read2st64_b32 v[218:219], v189 offset0:2 offset1:3
	global_store_dwordx4 v[214:215], v[210:213], off
	ds_read2st64_b32 v[210:211], v189 offset0:4 offset1:5
	ds_read2st64_b32 v[212:213], v189 offset0:6 offset1:7
	s_waitcnt lgkmcnt(3)
	v_mov_b32_e32 v214, v216
	s_waitcnt lgkmcnt(2)
	v_mov_b32_e32 v215, v218
	v_mov_b32_e32 v218, v217
	v_pk_mul_f32 v[216:217], v[166:167], v[218:219]
	s_waitcnt lgkmcnt(0)
	v_mov_b32_e32 v219, v212
	v_mov_b32_e32 v212, v211
	v_mov_b32_e32 v218, v210
	v_pk_mul_f32 v[210:211], v[168:169], v[212:213]
	v_pk_mul_f32 v[214:215], v[4:5], v[214:215]
	v_pk_mul_f32 v[218:219], v[164:165], v[218:219]
	v_bfe_u32 v209, v211, 16, 1
	v_bfe_u32 v212, v210, 16, 1
	v_bfe_u32 v213, v217, 16, 1
	v_bfe_u32 v220, v216, 16, 1
	v_add3_u32 v216, v216, v220, s55
	v_add3_u32 v217, v217, v213, s55
	v_add3_u32 v210, v210, v212, s55
	v_add3_u32 v209, v211, v209, s55
	v_bfe_u32 v211, v214, 16, 1
	v_bfe_u32 v212, v215, 16, 1
	v_bfe_u32 v213, v218, 16, 1
	v_bfe_u32 v220, v219, 16, 1
	v_add3_u32 v219, v219, v220, s55
	v_add3_u32 v213, v218, v213, s55
	v_add3_u32 v212, v215, v212, s55
	v_add3_u32 v211, v214, v211, s55
	v_lshrrev_b32_e32 v214, 16, v211
	v_lshrrev_b32_e32 v211, 16, v212
	v_lshrrev_b32_e32 v212, 16, v213
	v_lshrrev_b32_e32 v213, 16, v219
	v_and_or_b32 v213, v209, s56, v213
	v_or_b32_e32 v209, v207, v188
	v_and_or_b32 v212, v210, s56, v212
	v_and_or_b32 v210, v216, s56, v214
	v_and_or_b32 v214, v209, s63, v208
	v_cndmask_b32_e64 v209, v214, v209, s[4:5]
	v_add_u32_e32 v209, v209, v173
	v_mad_u64_u32 v[214:215], s[0:1], v209, v153, 0
	v_and_or_b32 v211, v217, s56, v211
	v_ashrrev_i32_e32 v217, 31, v209
	v_mov_b32_e32 v216, v215
	v_mad_u64_u32 v[216:217], s[0:1], v217, v153, v[216:217]
	v_mov_b32_e32 v215, v216
	v_lshl_add_u64 v[214:215], v[214:215], 1, v[154:155]
	v_lshl_add_u64 v[214:215], v[214:215], 0, v[170:171]
	v_lshl_add_u64 v[214:215], v[214:215], 0, v[162:163]
	ds_read2st64_b32 v[216:217], v191 offset1:1
	ds_read2st64_b32 v[218:219], v191 offset0:2 offset1:3
	global_store_dwordx4 v[214:215], v[210:213], off
	ds_read2st64_b32 v[210:211], v191 offset0:4 offset1:5
	ds_read2st64_b32 v[212:213], v191 offset0:6 offset1:7
	s_waitcnt lgkmcnt(3)
	v_mov_b32_e32 v214, v216
	s_waitcnt lgkmcnt(2)
	v_mov_b32_e32 v215, v218
	v_mov_b32_e32 v218, v217
	v_pk_mul_f32 v[216:217], v[166:167], v[218:219]
	s_waitcnt lgkmcnt(0)
	v_mov_b32_e32 v219, v212
	v_mov_b32_e32 v212, v211
	v_mov_b32_e32 v218, v210
	v_pk_mul_f32 v[210:211], v[168:169], v[212:213]
	v_pk_mul_f32 v[214:215], v[4:5], v[214:215]
	v_pk_mul_f32 v[218:219], v[164:165], v[218:219]
	v_bfe_u32 v209, v211, 16, 1
	v_bfe_u32 v212, v210, 16, 1
	v_bfe_u32 v213, v217, 16, 1
	v_bfe_u32 v220, v216, 16, 1
	v_add3_u32 v216, v216, v220, s55
	v_add3_u32 v217, v217, v213, s55
	v_add3_u32 v210, v210, v212, s55
	v_add3_u32 v209, v211, v209, s55
	v_bfe_u32 v211, v214, 16, 1
	v_bfe_u32 v212, v215, 16, 1
	v_bfe_u32 v213, v218, 16, 1
	v_bfe_u32 v220, v219, 16, 1
	v_add3_u32 v219, v219, v220, s55
	v_add3_u32 v213, v218, v213, s55
	v_add3_u32 v212, v215, v212, s55
	v_add3_u32 v211, v214, v211, s55
	v_lshrrev_b32_e32 v214, 16, v211
	v_lshrrev_b32_e32 v211, 16, v212
	v_lshrrev_b32_e32 v212, 16, v213
	v_lshrrev_b32_e32 v213, 16, v219
	v_and_or_b32 v213, v209, s56, v213
	v_or_b32_e32 v209, v207, v190
	v_and_or_b32 v212, v210, s56, v212
	v_and_or_b32 v210, v216, s56, v214
	v_and_or_b32 v214, v209, s64, v208
	v_cndmask_b32_e64 v209, v214, v209, s[4:5]
	v_add_u32_e32 v209, v209, v173
	v_mad_u64_u32 v[214:215], s[0:1], v209, v153, 0
	v_and_or_b32 v211, v217, s56, v211
	v_ashrrev_i32_e32 v217, 31, v209
	v_mov_b32_e32 v216, v215
	v_mad_u64_u32 v[216:217], s[0:1], v217, v153, v[216:217]
	v_mov_b32_e32 v215, v216
	v_lshl_add_u64 v[214:215], v[214:215], 1, v[154:155]
	v_lshl_add_u64 v[214:215], v[214:215], 0, v[170:171]
	v_lshl_add_u64 v[214:215], v[214:215], 0, v[162:163]
	ds_read2st64_b32 v[216:217], v193 offset1:1
	ds_read2st64_b32 v[218:219], v193 offset0:2 offset1:3
	global_store_dwordx4 v[214:215], v[210:213], off
	ds_read2st64_b32 v[210:211], v193 offset0:4 offset1:5
	ds_read2st64_b32 v[212:213], v193 offset0:6 offset1:7
	s_waitcnt lgkmcnt(3)
; #define LAS __attribute__((address_space(3)))
; __device__ __forceinline__ unsigned pk2(float lo, float hi) { return f2bf(lo) | (f2bf(hi) << 16); }
; __device__ __forceinline__ void cv_process(const CvDesc& d, int lane, const f32x4 (&v)[16], const f32x4& g0, const f32x4& g1, LAS float* scr) {
;     ...
;     for (int j = 0; j < 8; ++j) { const int n = (lane >> 3) + 8 * j; const LAS float* s = scr + (8 * c) * 64 + (n ^ (8 * c));
;         u32x4 o; o.x = pk2(s[0 * 64] * g0[0], s[1 * 64] * g0[1]); o.y = pk2(s[2 * 64] * g0[2], s[3 * 64] * g0[3]); o.z = pk2(s[4 * 64] * g1[0], s[5 * 64] * g1[1]); o.w = pk2(s[6 * 64] * g1[2], s[7 * 64] * g1[3]);
;         const int ng = n0 + n, drow = d.mode ? (((ng >> 7) << 8) + (ng & 127) + d.off) : (d.off + ng);
;         *(u32x4*)(d.dst + (size_t)drow * d.K + k0 + 8 * c) = o; }
	v_mov_b32_e32 v214, v216
	s_waitcnt lgkmcnt(2)
	v_mov_b32_e32 v215, v218
	v_mov_b32_e32 v218, v217
	v_pk_mul_f32 v[216:217], v[166:167], v[218:219]
	s_waitcnt lgkmcnt(0)
	v_mov_b32_e32 v219, v212
	v_mov_b32_e32 v212, v211
	v_mov_b32_e32 v218, v210
	v_pk_mul_f32 v[210:211], v[168:169], v[212:213]
	v_pk_mul_f32 v[214:215], v[4:5], v[214:215]
	v_pk_mul_f32 v[218:219], v[164:165], v[218:219]
	v_bfe_u32 v209, v211, 16, 1
	v_bfe_u32 v212, v210, 16, 1
	v_bfe_u32 v213, v217, 16, 1
	v_bfe_u32 v220, v216, 16, 1
	v_add3_u32 v216, v216, v220, s55
	v_add3_u32 v217, v217, v213, s55
	v_add3_u32 v210, v210, v212, s55
	v_add3_u32 v209, v211, v209, s55
	v_bfe_u32 v211, v214, 16, 1
	v_bfe_u32 v212, v215, 16, 1
	v_bfe_u32 v213, v218, 16, 1
	v_bfe_u32 v220, v219, 16, 1
	v_add3_u32 v219, v219, v220, s55
	v_add3_u32 v213, v218, v213, s55
	v_add3_u32 v212, v215, v212, s55
	v_add3_u32 v211, v214, v211, s55
	v_lshrrev_b32_e32 v214, 16, v211
	v_lshrrev_b32_e32 v211, 16, v212
	v_lshrrev_b32_e32 v212, 16, v213
	v_lshrrev_b32_e32 v213, 16, v219
	v_and_or_b32 v213, v209, s56, v213
	v_or_b32_e32 v209, v207, v192
	v_and_or_b32 v212, v210, s56, v212
	v_and_or_b32 v210, v216, s56, v214
	v_and_or_b32 v214, v209, s65, v208
	v_cndmask_b32_e64 v209, v214, v209, s[4:5]
	v_add_u32_e32 v209, v209, v173
	v_mad_u64_u32 v[214:215], s[0:1], v209, v153, 0
	v_and_or_b32 v211, v217, s56, v211
	v_ashrrev_i32_e32 v217, 31, v209
	v_mov_b32_e32 v216, v215
	v_mad_u64_u32 v[216:217], s[0:1], v217, v153, v[216:217]
	v_mov_b32_e32 v215, v216
	v_lshl_add_u64 v[214:215], v[214:215], 1, v[154:155]
	v_lshl_add_u64 v[214:215], v[214:215], 0, v[170:171]
	v_lshl_add_u64 v[214:215], v[214:215], 0, v[162:163]
	ds_read2st64_b32 v[216:217], v195 offset1:1
	ds_read2st64_b32 v[218:219], v195 offset0:2 offset1:3
	global_store_dwordx4 v[214:215], v[210:213], off
	ds_read2st64_b32 v[210:211], v195 offset0:4 offset1:5
	ds_read2st64_b32 v[212:213], v195 offset0:6 offset1:7
	s_waitcnt lgkmcnt(3)
	v_mov_b32_e32 v214, v216
	s_waitcnt lgkmcnt(2)
	v_mov_b32_e32 v215, v218
	v_mov_b32_e32 v218, v217
	v_pk_mul_f32 v[216:217], v[166:167], v[218:219]
	s_waitcnt lgkmcnt(0)
	v_mov_b32_e32 v219, v212
	v_mov_b32_e32 v212, v211
	v_mov_b32_e32 v218, v210
	v_pk_mul_f32 v[210:211], v[168:169], v[212:213]
	v_pk_mul_f32 v[214:215], v[4:5], v[214:215]
	v_pk_mul_f32 v[218:219], v[164:165], v[218:219]
	v_bfe_u32 v209, v211, 16, 1
	v_bfe_u32 v212, v210, 16, 1
	v_bfe_u32 v213, v217, 16, 1
	v_bfe_u32 v220, v216, 16, 1
	v_add3_u32 v216, v216, v220, s55
	v_add3_u32 v217, v217, v213, s55
	v_add3_u32 v210, v210, v212, s55
	v_add3_u32 v209, v211, v209, s55
	v_bfe_u32 v211, v214, 16, 1
	v_bfe_u32 v212, v215, 16, 1
	v_bfe_u32 v213, v218, 16, 1
	v_bfe_u32 v220, v219, 16, 1
	v_add3_u32 v219, v219, v220, s55
	v_add3_u32 v213, v218, v213, s55
	v_add3_u32 v212, v215, v212, s55
	v_add3_u32 v211, v214, v211, s55
	v_lshrrev_b32_e32 v214, 16, v211
	v_lshrrev_b32_e32 v211, 16, v212
	v_lshrrev_b32_e32 v212, 16, v213
	v_lshrrev_b32_e32 v213, 16, v219
	v_and_or_b32 v213, v209, s56, v213
	v_or_b32_e32 v209, v207, v194
	v_and_or_b32 v212, v210, s56, v212
	v_and_or_b32 v210, v216, s56, v214
	v_and_or_b32 v214, v209, s66, v208
	v_cndmask_b32_e64 v209, v214, v209, s[4:5]
	v_add_u32_e32 v209, v209, v173
	v_mad_u64_u32 v[214:215], s[0:1], v209, v153, 0
	v_and_or_b32 v211, v217, s56, v211
	v_ashrrev_i32_e32 v217, 31, v209
	v_mov_b32_e32 v216, v215
	v_mad_u64_u32 v[216:217], s[0:1], v217, v153, v[216:217]
	v_mov_b32_e32 v215, v216
	v_lshl_add_u64 v[214:215], v[214:215], 1, v[154:155]
	v_lshl_add_u64 v[214:215], v[214:215], 0, v[170:171]
	v_lshl_add_u64 v[214:215], v[214:215], 0, v[162:163]
	ds_read2st64_b32 v[216:217], v197 offset1:1
	ds_read2st64_b32 v[218:219], v197 offset0:2 offset1:3
	global_store_dwordx4 v[214:215], v[210:213], off
	ds_read2st64_b32 v[210:211], v197 offset0:4 offset1:5
	ds_read2st64_b32 v[212:213], v197 offset0:6 offset1:7
	s_waitcnt lgkmcnt(3)
	v_mov_b32_e32 v214, v216
	s_waitcnt lgkmcnt(2)
	v_mov_b32_e32 v215, v218
	v_mov_b32_e32 v218, v217
	v_pk_mul_f32 v[216:217], v[166:167], v[218:219]
	s_waitcnt lgkmcnt(0)
; #define LAS __attribute__((address_space(3)))
; __device__ __forceinline__ unsigned pk2(float lo, float hi) { return f2bf(lo) | (f2bf(hi) << 16); }
; #define LDS_WAIT() asm volatile("s_waitcnt lgkmcnt(0)" ::: "memory")
; __device__ __forceinline__ void cv_process(const CvDesc& d, int lane, const f32x4 (&v)[16], const f32x4& g0, const f32x4& g1, LAS float* scr) {
;     ...
;     for (int j = 0; j < 8; ++j) { const int n = (lane >> 3) + 8 * j; const LAS float* s = scr + (8 * c) * 64 + (n ^ (8 * c));
;         u32x4 o; o.x = pk2(s[0 * 64] * g0[0], s[1 * 64] * g0[1]); o.y = pk2(s[2 * 64] * g0[2], s[3 * 64] * g0[3]); o.z = pk2(s[4 * 64] * g1[0], s[5 * 64] * g1[1]); o.w = pk2(s[6 * 64] * g1[2], s[7 * 64] * g1[3]);
;         const int ng = n0 + n, drow = d.mode ? (((ng >> 7) << 8) + (ng & 127) + d.off) : (d.off + ng);
;         *(u32x4*)(d.dst + (size_t)drow * d.K + k0 + 8 * c) = o; }
;     LDS_WAIT(); asm volatile("" ::: "memory");
; __device__ __forceinline__ void convert_items(const Args& a, LAS unsigned char* lds, int first, int last, int worker, int nworkers) {
;     ...
;         if (!h1) break;
;         const int it2 = it1 + nworkers; const bool h2 = it2 < last;
;         if (h2) { d0 = cv_decode(a, it2); cv_load(d0, lane, va, ga0, ga1); }
	v_mov_b32_e32 v219, v212
	v_mov_b32_e32 v212, v211
	v_mov_b32_e32 v218, v210
	v_pk_mul_f32 v[210:211], v[168:169], v[212:213]
	v_pk_mul_f32 v[214:215], v[4:5], v[214:215]
	v_pk_mul_f32 v[218:219], v[164:165], v[218:219]
	v_bfe_u32 v209, v211, 16, 1
	v_bfe_u32 v212, v210, 16, 1
	v_bfe_u32 v213, v217, 16, 1
	v_bfe_u32 v220, v216, 16, 1
	v_add3_u32 v216, v216, v220, s55
	v_add3_u32 v217, v217, v213, s55
	v_add3_u32 v210, v210, v212, s55
	v_add3_u32 v209, v211, v209, s55
	v_bfe_u32 v211, v214, 16, 1
	v_bfe_u32 v212, v215, 16, 1
	v_bfe_u32 v213, v218, 16, 1
	v_bfe_u32 v220, v219, 16, 1
	v_add3_u32 v219, v219, v220, s55
	v_add3_u32 v213, v218, v213, s55
	v_add3_u32 v212, v215, v212, s55
	v_add3_u32 v211, v214, v211, s55
	v_lshrrev_b32_e32 v214, 16, v211
	v_lshrrev_b32_e32 v211, 16, v212
	v_lshrrev_b32_e32 v212, 16, v213
	v_lshrrev_b32_e32 v213, 16, v219
	v_and_or_b32 v213, v209, s56, v213
	v_or_b32_e32 v209, v207, v196
	v_and_or_b32 v212, v210, s56, v212
	v_and_or_b32 v210, v216, s56, v214
	v_and_or_b32 v214, v209, s67, v208
	v_cndmask_b32_e64 v209, v214, v209, s[4:5]
	v_add_u32_e32 v209, v209, v173
	v_mad_u64_u32 v[214:215], s[0:1], v209, v153, 0
	v_and_or_b32 v211, v217, s56, v211
	v_ashrrev_i32_e32 v217, 31, v209
	v_mov_b32_e32 v216, v215
	v_mad_u64_u32 v[216:217], s[0:1], v217, v153, v[216:217]
	v_mov_b32_e32 v215, v216
	v_lshl_add_u64 v[214:215], v[214:215], 1, v[154:155]
	v_lshl_add_u64 v[214:215], v[214:215], 0, v[170:171]
	v_lshl_add_u64 v[214:215], v[214:215], 0, v[162:163]
	global_store_dwordx4 v[214:215], v[210:213], off
	ds_read2st64_b32 v[210:211], v199 offset1:1
	ds_read2st64_b32 v[212:213], v199 offset0:2 offset1:3
	ds_read2st64_b32 v[214:215], v199 offset0:4 offset1:5
	ds_read2st64_b32 v[216:217], v199 offset0:6 offset1:7
	v_or_b32_e32 v207, v207, v198
	v_and_or_b32 v208, v207, s54, v208
	v_cndmask_b32_e64 v207, v208, v207, s[4:5]
	s_waitcnt lgkmcnt(3)
	v_mov_b32_e32 v208, v211
	s_waitcnt lgkmcnt(2)
	v_mov_b32_e32 v209, v213
	v_pk_mul_f32 v[166:167], v[166:167], v[208:209]
	s_waitcnt lgkmcnt(1)
	v_mov_b32_e32 v208, v215
	s_waitcnt lgkmcnt(0)
	v_mov_b32_e32 v209, v217
	v_mov_b32_e32 v211, v212
	v_pk_mul_f32 v[168:169], v[168:169], v[208:209]
	v_mov_b32_e32 v215, v216
	v_pk_mul_f32 v[4:5], v[4:5], v[210:211]
	v_pk_mul_f32 v[164:165], v[164:165], v[214:215]
	v_bfe_u32 v208, v169, 16, 1
	v_bfe_u32 v209, v168, 16, 1
	v_bfe_u32 v210, v167, 16, 1
	v_bfe_u32 v211, v166, 16, 1
	v_add3_u32 v211, v166, v211, s55
	v_add3_u32 v210, v167, v210, s55
	v_add3_u32 v166, v168, v209, s55
	v_add3_u32 v167, v169, v208, s55
	v_bfe_u32 v168, v4, 16, 1
	v_bfe_u32 v169, v5, 16, 1
	v_bfe_u32 v208, v164, 16, 1
	v_bfe_u32 v209, v165, 16, 1
	v_add3_u32 v165, v165, v209, s55
	v_add3_u32 v164, v164, v208, s55
	v_add3_u32 v5, v5, v169, s55
	v_add3_u32 v4, v4, v168, s55
	v_add_u32_e32 v207, v207, v173
	v_lshrrev_b32_e32 v4, 16, v4
	v_lshrrev_b32_e32 v5, 16, v5
	v_lshrrev_b32_e32 v164, 16, v164
	v_lshrrev_b32_e32 v165, 16, v165
	v_and_or_b32 v167, v167, s56, v165
	v_and_or_b32 v166, v166, s56, v164
	v_and_or_b32 v165, v210, s56, v5
	v_and_or_b32 v164, v211, s56, v4
	v_mad_u64_u32 v[4:5], s[0:1], v207, v153, 0
	v_ashrrev_i32_e32 v169, 31, v207
	v_mov_b32_e32 v168, v5
	v_mad_u64_u32 v[168:169], s[0:1], v169, v153, v[168:169]
	v_mov_b32_e32 v5, v168
	v_lshl_add_u64 v[4:5], v[4:5], 1, v[154:155]
	v_lshl_add_u64 v[4:5], v[4:5], 0, v[170:171]
	v_lshl_add_u64 v[4:5], v[4:5], 0, v[162:163]
	global_store_dwordx4 v[4:5], v[164:167], off
	s_waitcnt lgkmcnt(0)
	s_mov_b64 s[0:1], 0
	s_and_saveexec_b64 s[36:37], vcc
	s_cbranch_execz .LBB0_142
	s_mov_b32 s99, 0
	v_add_u32_e32 v168, s42, v206
	v_cmp_gt_i32_e32 vcc, s3, v168
	s_and_saveexec_b64 s[38:39], vcc
	s_cbranch_execz .LBB0_141
	s_mov_b32 s99, 1
	v_cmp_lt_i32_e64 s[4:5], s43, v168
	v_mov_b32_e32 v172, 1
	v_mov_b32_e32 v153, 0x800
	v_mov_b32_e32 v151, 0x1600
	v_mov_b64_e32 v[164:165], s[8:9]
	v_mov_b64_e32 v[154:155], s[44:45]
	v_mov_b64_e32 v[4:5], s[10:11]
	v_mov_b32_e32 v174, v168
	v_mov_b32_e32 v3, v168
	s_and_saveexec_b64 s[0:1], s[4:5]
	v_add_u32_e32 v3, 0xfffff500, v168
	v_mov_b32_e32 v172, 0
	v_mov_b64_e32 v[164:165], 0
	v_mov_b32_e32 v151, 64
	v_mov_b32_e32 v153, 64
	v_mov_b64_e32 v[154:155], 0
	v_mov_b64_e32 v[4:5], 0
	v_mov_b32_e32 v174, 0
	s_or_b64 exec, exec, s[0:1]
	s_mov_b64 s[46:47], -1
	v_mov_b32_e32 v173, 0
	s_mov_b64 s[50:51], -1
	s_and_saveexec_b64 s[0:1], s[4:5]
	s_cbranch_execz .LBB0_239
	v_cmp_lt_i32_e64 s[4:5], s43, v3
	v_mov_b32_e32 v15, 0x1600
	v_mov_b32_e32 v14, 0x800
	v_mov_b32_e32 v12, 1
	v_mov_b32_e32 v173, 0x80
	v_mov_b64_e32 v[6:7], s[12:13]
	v_mov_b64_e32 v[8:9], s[44:45]
	v_mov_b64_e32 v[10:11], s[8:9]
	v_mov_b32_e32 v13, v3
	s_and_saveexec_b64 s[52:53], s[4:5]
	s_cbranch_execz .LBB0_238
	v_add_u32_e32 v3, 0xfffff500, v3
	v_mov_b32_e32 v173, 0
	s_xor_b64 s[50:51], exec, -1
	v_mov_b32_e32 v13, v174
	v_mov_b32_e32 v12, v172
	v_mov_b64_e32 v[6:7], v[4:5]
	v_mov_b64_e32 v[8:9], v[154:155]
	v_mov_b64_e32 v[10:11], v[164:165]
	v_mov_b32_e32 v14, v153
	v_mov_b32_e32 v15, v151
